# grid barrier: each workgroup invalidates at arrival (no loads happen between arrival and release); the XCD leader invalidates before its write-back and cross-XCD arrival
# speedup vs baseline: 1.0109x; 1.0109x over previous
; __device__ __forceinline__ unsigned xb_add(unsigned* p, unsigned v) { return __hip_atomic_fetch_add(p, v, __ATOMIC_RELAXED, __HIP_MEMORY_SCOPE_AGENT); }
; __device__ __forceinline__ void xcd_barrier(const XcdBarrier& b) {
;     ...
;             __builtin_amdgcn_fence(__ATOMIC_ACQUIRE, "agent");
;             xb_add(&bar[XB_XGEN(b.x)], 1u);
;             asm volatile("s_waitcnt vmcnt(0)" ::: "memory");
.LBB0_18:
	s_or_b64 exec, exec, s[4:5]
	v_mov_b32_e32 v0, s44
	v_add_co_u32_e32 v2, vcc, 0x2000, v0
	v_mov_b32_e32 v0, s10
	s_nop 0
	v_addc_co_u32_e32 v3, vcc, 0, v0, vcc
	s_waitcnt vmcnt(0) lgkmcnt(0)
	flat_atomic_add v[2:3], v223 offset:1024
	s_waitcnt vmcnt(0)

; __device__ __forceinline__ unsigned xb_ld(unsigned* p)              { return __hip_atomic_load(p, __ATOMIC_RELAXED, __HIP_MEMORY_SCOPE_AGENT); }
; __device__ __forceinline__ unsigned xb_add(unsigned* p, unsigned v) { return __hip_atomic_fetch_add(p, v, __ATOMIC_RELAXED, __HIP_MEMORY_SCOPE_AGENT); }
; #define XB_SPIN(cond, bar) do { unsigned _sp = 0; while (cond) { __builtin_amdgcn_s_sleep(1); \
;     if ((++_sp & 255u) == 0u) { if (xb_ld(&(bar)[XB_TMO])) break; if (_sp > XB_SPIN_CAP) { atomicAdd(&(bar)[XB_TMO], 1u); break; } } } } while (0)
; __device__ __forceinline__ void xcd_barrier(const XcdBarrier& b) {
;     ...
;         const unsigned old = xb_add(&bar[XB_XSUB(b.x)], 1u);
;         const unsigned gen = old / nloc;
;         if (old + 1u == (gen + 1u) * nloc) {
;             __builtin_amdgcn_fence(__ATOMIC_RELEASE, "agent");
;             asm volatile("s_waitcnt vmcnt(0)" ::: "memory");
;             const unsigned og = xb_add(&bar[XB_TOP], 1u);
;             const unsigned tg = og / nx;
;             if (og + 1u == (tg + 1u) * nx) xb_add(&bar[XB_TOPGEN], 1u);
;             else XB_SPIN(xb_ld(&bar[XB_TOPGEN]) == tg, bar);
;             __builtin_amdgcn_fence(__ATOMIC_ACQUIRE, "agent");
;             xb_add(&bar[XB_XGEN(b.x)], 1u);
;             asm volatile("s_waitcnt vmcnt(0)" ::: "memory");
;         } else {
;             XB_SPIN(xb_ld(&bar[XB_XGEN(b.x)]) == gen, bar);
;             __builtin_amdgcn_fence(__ATOMIC_ACQUIRE, "agent");
;             asm volatile("s_waitcnt vmcnt(0)" ::: "memory");
.LBB0_192:
	v_readlane_b32 s0, v252, 41
	s_lshl_b32 s0, s0, 2
	s_add_u32 s48, s4, s0
	s_addc_u32 s10, s5, 0
	v_mov_b32_e32 v3, s48
	v_add_co_u32_e32 v4, vcc, 0x1000, v3
	v_mov_b32_e32 v3, s10
	s_nop 0
	v_addc_co_u32_e32 v5, vcc, 0, v3, vcc
	flat_atomic_add v3, v[4:5], v223 offset:1024 sc0
	v_cvt_f32_u32_e32 v4, v2
	v_sub_u32_e32 v5, 0, v2
	v_rcp_iflag_f32_e32 v4, v4
	s_nop 0
	v_mul_f32_e32 v4, 0x4f7ffffe, v4
	v_cvt_u32_f32_e32 v4, v4
	v_mul_lo_u32 v5, v5, v4
	v_mul_hi_u32 v5, v4, v5
	v_add_u32_e32 v4, v4, v5
	s_waitcnt vmcnt(0) lgkmcnt(0)
	v_mul_hi_u32 v4, v3, v4
	v_mul_lo_u32 v5, v4, v2
	v_add_u32_e32 v6, 1, v3
	v_sub_u32_e32 v3, v3, v5
	v_add_u32_e32 v7, 1, v4
	v_sub_u32_e32 v5, v3, v2
	v_cmp_ge_u32_e32 vcc, v3, v2
	s_nop 1
	v_cndmask_b32_e32 v4, v4, v7, vcc
	v_cndmask_b32_e32 v3, v3, v5, vcc
	v_add_u32_e32 v5, 1, v4
	v_cmp_ge_u32_e32 vcc, v3, v2
	s_nop 1
	v_cndmask_b32_e32 v3, v4, v5, vcc
	v_mad_u64_u32 v[4:5], s[6:7], v2, v3, v[2:3]
	v_cmp_ne_u32_e32 vcc, v6, v4
	s_and_saveexec_b64 s[6:7], vcc
	s_xor_b64 s[34:35], exec, s[6:7]
	s_cbranch_execz .LBB0_205
	buffer_inv sc1
	s_waitcnt vmcnt(0)
	s_add_u32 s20, s4, 0x3500
	s_addc_u32 s21, s5, 0
	v_mov_b64_e32 v[4:5], s[20:21]
	flat_load_dword v0, v[4:5] sc1
	s_waitcnt vmcnt(0) lgkmcnt(0)
	v_cmp_eq_u32_e32 vcc, v0, v3
	s_and_saveexec_b64 s[22:23], vcc
	s_cbranch_execz .LBB0_204
	s_mov_b32 s49, 1
	s_mov_b64 s[6:7], 0
	s_branch .LBB0_196

; __device__ __forceinline__ unsigned xb_ld(unsigned* p)              { return __hip_atomic_load(p, __ATOMIC_RELAXED, __HIP_MEMORY_SCOPE_AGENT); }
; __device__ __forceinline__ unsigned xb_add(unsigned* p, unsigned v) { return __hip_atomic_fetch_add(p, v, __ATOMIC_RELAXED, __HIP_MEMORY_SCOPE_AGENT); }
; #define XB_SPIN(cond, bar) do { unsigned _sp = 0; while (cond) { __builtin_amdgcn_s_sleep(1); \
;     if ((++_sp & 255u) == 0u) { if (xb_ld(&(bar)[XB_TMO])) break; if (_sp > XB_SPIN_CAP) { atomicAdd(&(bar)[XB_TMO], 1u); break; } } } } while (0)
; __device__ __forceinline__ void xcd_barrier(const XcdBarrier& b) {
;     ...
;         if (old + 1u == (gen + 1u) * nloc) {
;             __builtin_amdgcn_fence(__ATOMIC_RELEASE, "agent");
;             asm volatile("s_waitcnt vmcnt(0)" ::: "memory");
;             const unsigned og = xb_add(&bar[XB_TOP], 1u);
;             const unsigned tg = og / nx;
;             if (og + 1u == (tg + 1u) * nx) xb_add(&bar[XB_TOPGEN], 1u);
;             else XB_SPIN(xb_ld(&bar[XB_TOPGEN]) == tg, bar);
;             __builtin_amdgcn_fence(__ATOMIC_ACQUIRE, "agent");
;             xb_add(&bar[XB_XGEN(b.x)], 1u);
;             asm volatile("s_waitcnt vmcnt(0)" ::: "memory");
;         } else {
;             XB_SPIN(xb_ld(&bar[XB_XGEN(b.x)]) == gen, bar);
;             __builtin_amdgcn_fence(__ATOMIC_ACQUIRE, "agent");
;             asm volatile("s_waitcnt vmcnt(0)" ::: "memory");
.LBB0_204:
	s_or_b64 exec, exec, s[22:23]
	s_waitcnt vmcnt(0) lgkmcnt(0)
	s_waitcnt vmcnt(0)
.LBB0_205:
	s_andn2_saveexec_b64 s[6:7], s[34:35]
	s_cbranch_execz .LBB0_221
	v_mov_b32_e32 v2, s4
	v_add_co_u32_e32 v2, vcc, 0x3000, v2
	v_mov_b32_e32 v3, s5
	buffer_inv sc1
	buffer_wbl2 sc1
	s_waitcnt vmcnt(0)
	v_addc_co_u32_e32 v3, vcc, 0, v3, vcc
	flat_atomic_add v2, v[2:3], v223 offset:1024 sc0
	v_cvt_f32_u32_e32 v3, v0
	v_sub_u32_e32 v4, 0, v0
	s_add_u32 s34, s4, 0x3500
	s_addc_u32 s35, s5, 0
	v_rcp_iflag_f32_e32 v3, v3
	s_mov_b64 s[6:7], -1
	v_mul_f32_e32 v3, 0x4f7ffffe, v3
	v_cvt_u32_f32_e32 v3, v3
	v_mul_lo_u32 v4, v4, v3
	v_mul_hi_u32 v4, v3, v4
	v_add_u32_e32 v3, v3, v4
	s_waitcnt vmcnt(0) lgkmcnt(0)
	v_mul_hi_u32 v3, v2, v3
	v_mul_lo_u32 v4, v3, v0
	v_add_u32_e32 v5, 1, v2
	v_sub_u32_e32 v2, v2, v4
	v_add_u32_e32 v6, 1, v3
	v_sub_u32_e32 v4, v2, v0
	v_cmp_ge_u32_e32 vcc, v2, v0
	s_nop 1
	v_cndmask_b32_e32 v3, v3, v6, vcc
	v_cndmask_b32_e32 v2, v2, v4, vcc
	v_add_u32_e32 v4, 1, v3
	v_cmp_ge_u32_e32 vcc, v2, v0
	s_nop 1
	v_cndmask_b32_e32 v4, v3, v4, vcc
	v_mad_u64_u32 v[2:3], s[20:21], v0, v4, v[0:1]
	v_cmp_ne_u32_e32 vcc, v5, v2
	v_mov_b64_e32 v[2:3], s[34:35]
	s_and_saveexec_b64 s[36:37], vcc
	s_cbranch_execz .LBB0_218
	v_mov_b64_e32 v[2:3], s[34:35]
	flat_load_dword v0, v[2:3] sc1
	s_mov_b64 s[6:7], 0
	s_waitcnt vmcnt(0) lgkmcnt(0)
	v_cmp_eq_u32_e32 vcc, v0, v4
	s_and_saveexec_b64 s[22:23], vcc
	s_cbranch_execz .LBB0_217
	s_add_u32 s20, s4, 0x200
	s_addc_u32 s21, s5, 0
	s_mov_b32 s46, 1
	s_mov_b64 s[4:5], 0
	s_branch .LBB0_210

; __device__ __forceinline__ unsigned xb_add(unsigned* p, unsigned v) { return __hip_atomic_fetch_add(p, v, __ATOMIC_RELAXED, __HIP_MEMORY_SCOPE_AGENT); }
; __device__ __forceinline__ void xcd_barrier(const XcdBarrier& b) {
;     ...
;             __builtin_amdgcn_fence(__ATOMIC_ACQUIRE, "agent");
;             xb_add(&bar[XB_XGEN(b.x)], 1u);
;             asm volatile("s_waitcnt vmcnt(0)" ::: "memory");
.LBB0_220:
	s_or_b64 exec, exec, s[4:5]
	v_mov_b32_e32 v0, s48
	v_add_co_u32_e32 v2, vcc, 0x2000, v0
	v_mov_b32_e32 v0, s10
	s_nop 0
	v_addc_co_u32_e32 v3, vcc, 0, v0, vcc
	s_waitcnt vmcnt(0) lgkmcnt(0)
	flat_atomic_add v[2:3], v223 offset:1024
	s_waitcnt vmcnt(0)

; __device__ __forceinline__ unsigned xb_ld(unsigned* p)              { return __hip_atomic_load(p, __ATOMIC_RELAXED, __HIP_MEMORY_SCOPE_AGENT); }
; __device__ __forceinline__ unsigned xb_add(unsigned* p, unsigned v) { return __hip_atomic_fetch_add(p, v, __ATOMIC_RELAXED, __HIP_MEMORY_SCOPE_AGENT); }
; #define XB_SPIN(cond, bar) do { unsigned _sp = 0; while (cond) { __builtin_amdgcn_s_sleep(1); \
;     if ((++_sp & 255u) == 0u) { if (xb_ld(&(bar)[XB_TMO])) break; if (_sp > XB_SPIN_CAP) { atomicAdd(&(bar)[XB_TMO], 1u); break; } } } } while (0)
; __device__ __forceinline__ void xcd_barrier(const XcdBarrier& b) {
;     ...
;         const unsigned old = xb_add(&bar[XB_XSUB(b.x)], 1u);
;         const unsigned gen = old / nloc;
;         if (old + 1u == (gen + 1u) * nloc) {
;             __builtin_amdgcn_fence(__ATOMIC_RELEASE, "agent");
;             asm volatile("s_waitcnt vmcnt(0)" ::: "memory");
;             const unsigned og = xb_add(&bar[XB_TOP], 1u);
;             const unsigned tg = og / nx;
;             if (og + 1u == (tg + 1u) * nx) xb_add(&bar[XB_TOPGEN], 1u);
;             else XB_SPIN(xb_ld(&bar[XB_TOPGEN]) == tg, bar);
;             __builtin_amdgcn_fence(__ATOMIC_ACQUIRE, "agent");
;             xb_add(&bar[XB_XGEN(b.x)], 1u);
;             asm volatile("s_waitcnt vmcnt(0)" ::: "memory");
;         } else {
;             XB_SPIN(xb_ld(&bar[XB_XGEN(b.x)]) == gen, bar);
;             __builtin_amdgcn_fence(__ATOMIC_ACQUIRE, "agent");
;             asm volatile("s_waitcnt vmcnt(0)" ::: "memory");
.LBB0_290:
	v_readlane_b32 s0, v252, 41
	s_lshl_b32 s0, s0, 2
	s_add_u32 s48, s4, s0
	s_addc_u32 s10, s5, 0
	v_mov_b32_e32 v3, s48
	v_add_co_u32_e32 v4, vcc, 0x1000, v3
	v_mov_b32_e32 v3, s10
	s_nop 0
	v_addc_co_u32_e32 v5, vcc, 0, v3, vcc
	flat_atomic_add v4, v[4:5], v223 offset:1024 sc0
	v_cvt_f32_u32_e32 v3, v2
	v_sub_u32_e32 v5, 0, v2
	v_rcp_iflag_f32_e32 v3, v3
	s_nop 0
	v_mul_f32_e32 v3, 0x4f7ffffe, v3
	v_cvt_u32_f32_e32 v3, v3
	v_mul_lo_u32 v5, v5, v3
	v_mul_hi_u32 v5, v3, v5
	v_add_u32_e32 v3, v3, v5
	s_waitcnt vmcnt(0) lgkmcnt(0)
	v_mul_hi_u32 v3, v4, v3
	v_mul_lo_u32 v5, v3, v2
	v_sub_u32_e32 v5, v4, v5
	v_cmp_ge_u32_e32 vcc, v5, v2
	v_add_u32_e32 v6, 1, v3
	s_nop 0
	v_cndmask_b32_e32 v3, v3, v6, vcc
	v_sub_u32_e32 v6, v5, v2
	v_cndmask_b32_e32 v5, v5, v6, vcc
	v_cmp_ge_u32_e32 vcc, v5, v2
	v_add_u32_e32 v5, 1, v3
	v_add_u32_e32 v6, 1, v4
	v_cndmask_b32_e32 v3, v3, v5, vcc
	v_mad_u64_u32 v[4:5], s[6:7], v2, v3, v[2:3]
	v_cmp_ne_u32_e32 vcc, v6, v4
	s_and_saveexec_b64 s[6:7], vcc
	s_xor_b64 s[34:35], exec, s[6:7]
	s_cbranch_execz .LBB0_303
	buffer_inv sc1
	s_waitcnt vmcnt(0)
	s_add_u32 s20, s4, 0x3500
	s_addc_u32 s21, s5, 0
	v_mov_b64_e32 v[4:5], s[20:21]
	flat_load_dword v0, v[4:5] sc1
	s_waitcnt vmcnt(0) lgkmcnt(0)
	v_cmp_eq_u32_e32 vcc, v0, v3
	s_and_saveexec_b64 s[22:23], vcc
	s_cbranch_execz .LBB0_302
	s_mov_b32 s49, 1
	s_mov_b64 s[6:7], 0
	s_branch .LBB0_294

; __device__ __forceinline__ unsigned xb_ld(unsigned* p)              { return __hip_atomic_load(p, __ATOMIC_RELAXED, __HIP_MEMORY_SCOPE_AGENT); }
; __device__ __forceinline__ unsigned xb_add(unsigned* p, unsigned v) { return __hip_atomic_fetch_add(p, v, __ATOMIC_RELAXED, __HIP_MEMORY_SCOPE_AGENT); }
; #define XB_SPIN(cond, bar) do { unsigned _sp = 0; while (cond) { __builtin_amdgcn_s_sleep(1); \
;     if ((++_sp & 255u) == 0u) { if (xb_ld(&(bar)[XB_TMO])) break; if (_sp > XB_SPIN_CAP) { atomicAdd(&(bar)[XB_TMO], 1u); break; } } } } while (0)
; __device__ __forceinline__ void xcd_barrier(const XcdBarrier& b) {
;     ...
;         if (old + 1u == (gen + 1u) * nloc) {
;             __builtin_amdgcn_fence(__ATOMIC_RELEASE, "agent");
;             asm volatile("s_waitcnt vmcnt(0)" ::: "memory");
;             const unsigned og = xb_add(&bar[XB_TOP], 1u);
;             const unsigned tg = og / nx;
;             if (og + 1u == (tg + 1u) * nx) xb_add(&bar[XB_TOPGEN], 1u);
;             else XB_SPIN(xb_ld(&bar[XB_TOPGEN]) == tg, bar);
.LBB0_303:
	s_andn2_saveexec_b64 s[6:7], s[34:35]
	s_cbranch_execz .LBB0_319
	v_mov_b32_e32 v2, s4
	v_add_co_u32_e32 v2, vcc, 0x3000, v2
	v_mov_b32_e32 v3, s5
	buffer_inv sc1
	buffer_wbl2 sc1
	s_waitcnt vmcnt(0)
	v_addc_co_u32_e32 v3, vcc, 0, v3, vcc
	flat_atomic_add v2, v[2:3], v223 offset:1024 sc0
	v_cvt_f32_u32_e32 v3, v0
	v_sub_u32_e32 v4, 0, v0
	s_add_u32 s34, s4, 0x3500
	s_addc_u32 s35, s5, 0
	v_rcp_iflag_f32_e32 v3, v3
	s_nop 0
	v_mul_f32_e32 v3, 0x4f7ffffe, v3
	v_cvt_u32_f32_e32 v3, v3
	v_mul_lo_u32 v4, v4, v3
	v_mul_hi_u32 v4, v3, v4
	v_add_u32_e32 v3, v3, v4
	s_waitcnt vmcnt(0) lgkmcnt(0)
	v_mul_hi_u32 v3, v2, v3
	v_mul_lo_u32 v4, v3, v0
	v_sub_u32_e32 v4, v2, v4
	v_cmp_ge_u32_e32 vcc, v4, v0
	v_add_u32_e32 v5, 1, v3
	s_nop 0
	v_cndmask_b32_e32 v3, v3, v5, vcc
	v_sub_u32_e32 v5, v4, v0
	v_cndmask_b32_e32 v4, v4, v5, vcc
	v_cmp_ge_u32_e32 vcc, v4, v0
	v_add_u32_e32 v4, 1, v3
	v_add_u32_e32 v5, 1, v2
	v_cndmask_b32_e32 v4, v3, v4, vcc
	v_mad_u64_u32 v[2:3], s[6:7], v0, v4, v[0:1]
	v_cmp_ne_u32_e32 vcc, v5, v2
	s_mov_b64 s[6:7], -1
	v_mov_b64_e32 v[2:3], s[34:35]
	s_and_saveexec_b64 s[36:37], vcc
	s_cbranch_execz .LBB0_316
	v_mov_b64_e32 v[2:3], s[34:35]
	flat_load_dword v0, v[2:3] sc1
	s_mov_b64 s[6:7], 0
	s_waitcnt vmcnt(0) lgkmcnt(0)
	v_cmp_eq_u32_e32 vcc, v0, v4
	s_and_saveexec_b64 s[22:23], vcc
	s_cbranch_execz .LBB0_315
	s_add_u32 s20, s4, 0x200
	s_addc_u32 s21, s5, 0
	s_mov_b32 s46, 1
	s_mov_b64 s[4:5], 0
	s_branch .LBB0_308

; __device__ __forceinline__ unsigned xb_ld(unsigned* p)              { return __hip_atomic_load(p, __ATOMIC_RELAXED, __HIP_MEMORY_SCOPE_AGENT); }
; __device__ __forceinline__ unsigned xb_add(unsigned* p, unsigned v) { return __hip_atomic_fetch_add(p, v, __ATOMIC_RELAXED, __HIP_MEMORY_SCOPE_AGENT); }
; #define XB_SPIN(cond, bar) do { unsigned _sp = 0; while (cond) { __builtin_amdgcn_s_sleep(1); \
;     if ((++_sp & 255u) == 0u) { if (xb_ld(&(bar)[XB_TMO])) break; if (_sp > XB_SPIN_CAP) { atomicAdd(&(bar)[XB_TMO], 1u); break; } } } } while (0)
; __device__ __forceinline__ void xcd_barrier(const XcdBarrier& b) {
;     ...
;         const unsigned old = xb_add(&bar[XB_XSUB(b.x)], 1u);
;         const unsigned gen = old / nloc;
;         if (old + 1u == (gen + 1u) * nloc) {
;             __builtin_amdgcn_fence(__ATOMIC_RELEASE, "agent");
;             asm volatile("s_waitcnt vmcnt(0)" ::: "memory");
;             const unsigned og = xb_add(&bar[XB_TOP], 1u);
;             const unsigned tg = og / nx;
;             if (og + 1u == (tg + 1u) * nx) xb_add(&bar[XB_TOPGEN], 1u);
;             else XB_SPIN(xb_ld(&bar[XB_TOPGEN]) == tg, bar);
;             __builtin_amdgcn_fence(__ATOMIC_ACQUIRE, "agent");
;             xb_add(&bar[XB_XGEN(b.x)], 1u);
;             asm volatile("s_waitcnt vmcnt(0)" ::: "memory");
;         } else {
;             XB_SPIN(xb_ld(&bar[XB_XGEN(b.x)]) == gen, bar);
;             __builtin_amdgcn_fence(__ATOMIC_ACQUIRE, "agent");
;             asm volatile("s_waitcnt vmcnt(0)" ::: "memory");
.LBB0_459:
	v_readlane_b32 s0, v252, 41
	s_lshl_b32 s0, s0, 2
	s_add_u32 s44, s4, s0
	s_addc_u32 s10, s5, 0
	v_mov_b32_e32 v3, s44
	v_add_co_u32_e32 v4, vcc, 0x1000, v3
	v_mov_b32_e32 v3, s10
	s_nop 0
	v_addc_co_u32_e32 v5, vcc, 0, v3, vcc
	flat_atomic_add v4, v[4:5], v223 offset:1024 sc0
	v_cvt_f32_u32_e32 v3, v2
	v_sub_u32_e32 v5, 0, v2
	v_rcp_iflag_f32_e32 v3, v3
	s_nop 0
	v_mul_f32_e32 v3, 0x4f7ffffe, v3
	v_cvt_u32_f32_e32 v3, v3
	v_mul_lo_u32 v5, v5, v3
	v_mul_hi_u32 v5, v3, v5
	v_add_u32_e32 v3, v3, v5
	s_waitcnt vmcnt(0) lgkmcnt(0)
	v_mul_hi_u32 v3, v4, v3
	v_mul_lo_u32 v5, v3, v2
	v_sub_u32_e32 v5, v4, v5
	v_cmp_ge_u32_e32 vcc, v5, v2
	v_add_u32_e32 v6, 1, v3
	s_nop 0
	v_cndmask_b32_e32 v3, v3, v6, vcc
	v_sub_u32_e32 v6, v5, v2
	v_cndmask_b32_e32 v5, v5, v6, vcc
	v_cmp_ge_u32_e32 vcc, v5, v2
	v_add_u32_e32 v5, 1, v3
	v_add_u32_e32 v6, 1, v4
	v_cndmask_b32_e32 v3, v3, v5, vcc
	v_mad_u64_u32 v[4:5], s[6:7], v2, v3, v[2:3]
	v_cmp_ne_u32_e32 vcc, v6, v4
	s_and_saveexec_b64 s[6:7], vcc
	s_xor_b64 s[8:9], exec, s[6:7]
	s_cbranch_execz .LBB0_472
	buffer_inv sc1
	s_waitcnt vmcnt(0)
	s_add_u32 s20, s4, 0x3500
	s_addc_u32 s21, s5, 0
	v_mov_b64_e32 v[4:5], s[20:21]
	flat_load_dword v0, v[4:5] sc1
	s_waitcnt vmcnt(0) lgkmcnt(0)
	v_cmp_eq_u32_e32 vcc, v0, v3
	s_and_saveexec_b64 s[12:13], vcc
	s_cbranch_execz .LBB0_471
	s_mov_b32 s45, 1
	s_mov_b64 s[6:7], 0
	s_branch .LBB0_463

; __device__ __forceinline__ unsigned xb_ld(unsigned* p)              { return __hip_atomic_load(p, __ATOMIC_RELAXED, __HIP_MEMORY_SCOPE_AGENT); }
; __device__ __forceinline__ unsigned xb_add(unsigned* p, unsigned v) { return __hip_atomic_fetch_add(p, v, __ATOMIC_RELAXED, __HIP_MEMORY_SCOPE_AGENT); }
; #define XB_SPIN(cond, bar) do { unsigned _sp = 0; while (cond) { __builtin_amdgcn_s_sleep(1); \
;     if ((++_sp & 255u) == 0u) { if (xb_ld(&(bar)[XB_TMO])) break; if (_sp > XB_SPIN_CAP) { atomicAdd(&(bar)[XB_TMO], 1u); break; } } } } while (0)
; __device__ __forceinline__ void xcd_barrier(const XcdBarrier& b) {
;     ...
;         if (old + 1u == (gen + 1u) * nloc) {
;             __builtin_amdgcn_fence(__ATOMIC_RELEASE, "agent");
;             asm volatile("s_waitcnt vmcnt(0)" ::: "memory");
;             const unsigned og = xb_add(&bar[XB_TOP], 1u);
;             const unsigned tg = og / nx;
;             if (og + 1u == (tg + 1u) * nx) xb_add(&bar[XB_TOPGEN], 1u);
;             else XB_SPIN(xb_ld(&bar[XB_TOPGEN]) == tg, bar);
;             __builtin_amdgcn_fence(__ATOMIC_ACQUIRE, "agent");
;             xb_add(&bar[XB_XGEN(b.x)], 1u);
;             asm volatile("s_waitcnt vmcnt(0)" ::: "memory");
;         } else {
;             XB_SPIN(xb_ld(&bar[XB_XGEN(b.x)]) == gen, bar);
;             __builtin_amdgcn_fence(__ATOMIC_ACQUIRE, "agent");
;             asm volatile("s_waitcnt vmcnt(0)" ::: "memory");
.LBB0_471:
	s_or_b64 exec, exec, s[12:13]
	s_waitcnt vmcnt(0) lgkmcnt(0)
	s_waitcnt vmcnt(0)
.LBB0_472:
	s_andn2_saveexec_b64 s[6:7], s[8:9]
	s_cbranch_execz .LBB0_488
	v_mov_b32_e32 v2, s4
	v_add_co_u32_e32 v2, vcc, 0x3000, v2
	v_mov_b32_e32 v3, s5
	buffer_inv sc1
	buffer_wbl2 sc1
	s_waitcnt vmcnt(0)
	v_addc_co_u32_e32 v3, vcc, 0, v3, vcc
	flat_atomic_add v2, v[2:3], v223 offset:1024 sc0
	v_cvt_f32_u32_e32 v3, v0
	v_sub_u32_e32 v4, 0, v0
	s_add_u32 s8, s4, 0x3500
	s_addc_u32 s9, s5, 0
	v_rcp_iflag_f32_e32 v3, v3
	s_nop 0
	v_mul_f32_e32 v3, 0x4f7ffffe, v3
	v_cvt_u32_f32_e32 v3, v3
	v_mul_lo_u32 v4, v4, v3
	v_mul_hi_u32 v4, v3, v4
	v_add_u32_e32 v3, v3, v4
	s_waitcnt vmcnt(0) lgkmcnt(0)
	v_mul_hi_u32 v3, v2, v3
	v_mul_lo_u32 v4, v3, v0
	v_sub_u32_e32 v4, v2, v4
	v_cmp_ge_u32_e32 vcc, v4, v0
	v_add_u32_e32 v5, 1, v3
	s_nop 0
	v_cndmask_b32_e32 v3, v3, v5, vcc
	v_sub_u32_e32 v5, v4, v0
	v_cndmask_b32_e32 v4, v4, v5, vcc
	v_cmp_ge_u32_e32 vcc, v4, v0
	v_add_u32_e32 v4, 1, v3
	v_add_u32_e32 v5, 1, v2
	v_cndmask_b32_e32 v4, v3, v4, vcc
	v_mad_u64_u32 v[2:3], s[6:7], v0, v4, v[0:1]
	v_cmp_ne_u32_e32 vcc, v5, v2
	s_mov_b64 s[6:7], -1
	v_mov_b64_e32 v[2:3], s[8:9]
	s_and_saveexec_b64 s[12:13], vcc
	s_cbranch_execz .LBB0_485
	v_mov_b64_e32 v[2:3], s[8:9]
	flat_load_dword v0, v[2:3] sc1
	s_mov_b64 s[6:7], 0
	s_waitcnt vmcnt(0) lgkmcnt(0)
	v_cmp_eq_u32_e32 vcc, v0, v4
	s_and_saveexec_b64 s[22:23], vcc
	s_cbranch_execz .LBB0_484
	s_add_u32 s20, s4, 0x200
	s_addc_u32 s21, s5, 0
	s_mov_b32 s42, 1
	s_mov_b64 s[4:5], 0
	s_branch .LBB0_477

; __device__ __forceinline__ unsigned xb_ld(unsigned* p)              { return __hip_atomic_load(p, __ATOMIC_RELAXED, __HIP_MEMORY_SCOPE_AGENT); }
; __device__ __forceinline__ unsigned xb_add(unsigned* p, unsigned v) { return __hip_atomic_fetch_add(p, v, __ATOMIC_RELAXED, __HIP_MEMORY_SCOPE_AGENT); }
; #define XB_SPIN(cond, bar) do { unsigned _sp = 0; while (cond) { __builtin_amdgcn_s_sleep(1); \
;     if ((++_sp & 255u) == 0u) { if (xb_ld(&(bar)[XB_TMO])) break; if (_sp > XB_SPIN_CAP) { atomicAdd(&(bar)[XB_TMO], 1u); break; } } } } while (0)
; __device__ __forceinline__ void xcd_barrier(const XcdBarrier& b) {
;     ...
;         const unsigned old = xb_add(&bar[XB_XSUB(b.x)], 1u);
;         const unsigned gen = old / nloc;
;         if (old + 1u == (gen + 1u) * nloc) {
;             __builtin_amdgcn_fence(__ATOMIC_RELEASE, "agent");
;             asm volatile("s_waitcnt vmcnt(0)" ::: "memory");
;             const unsigned og = xb_add(&bar[XB_TOP], 1u);
;             const unsigned tg = og / nx;
;             if (og + 1u == (tg + 1u) * nx) xb_add(&bar[XB_TOPGEN], 1u);
;             else XB_SPIN(xb_ld(&bar[XB_TOPGEN]) == tg, bar);
;             __builtin_amdgcn_fence(__ATOMIC_ACQUIRE, "agent");
;             xb_add(&bar[XB_XGEN(b.x)], 1u);
;             asm volatile("s_waitcnt vmcnt(0)" ::: "memory");
;         } else {
;             XB_SPIN(xb_ld(&bar[XB_XGEN(b.x)]) == gen, bar);
;             __builtin_amdgcn_fence(__ATOMIC_ACQUIRE, "agent");
;             asm volatile("s_waitcnt vmcnt(0)" ::: "memory");
.LBB0_831:
	v_readlane_b32 s0, v252, 41
	s_lshl_b32 s0, s0, 2
	s_add_u32 s44, s4, s0
	s_addc_u32 s10, s5, 0
	v_mov_b32_e32 v3, s44
	v_add_co_u32_e32 v4, vcc, 0x1000, v3
	v_mov_b32_e32 v3, s10
	s_nop 0
	v_addc_co_u32_e32 v5, vcc, 0, v3, vcc
	flat_atomic_add v4, v[4:5], v223 offset:1024 sc0
	v_cvt_f32_u32_e32 v3, v2
	v_sub_u32_e32 v5, 0, v2
	v_rcp_iflag_f32_e32 v3, v3
	s_nop 0
	v_mul_f32_e32 v3, 0x4f7ffffe, v3
	v_cvt_u32_f32_e32 v3, v3
	v_mul_lo_u32 v5, v5, v3
	v_mul_hi_u32 v5, v3, v5
	v_add_u32_e32 v3, v3, v5
	s_waitcnt vmcnt(0) lgkmcnt(0)
	v_mul_hi_u32 v3, v4, v3
	v_mul_lo_u32 v5, v3, v2
	v_sub_u32_e32 v5, v4, v5
	v_cmp_ge_u32_e32 vcc, v5, v2
	v_add_u32_e32 v6, 1, v3
	s_nop 0
	v_cndmask_b32_e32 v3, v3, v6, vcc
	v_sub_u32_e32 v6, v5, v2
	v_cndmask_b32_e32 v5, v5, v6, vcc
	v_cmp_ge_u32_e32 vcc, v5, v2
	v_add_u32_e32 v5, 1, v3
	v_add_u32_e32 v6, 1, v4
	v_cndmask_b32_e32 v3, v3, v5, vcc
	v_mad_u64_u32 v[4:5], s[0:1], v2, v3, v[2:3]
	v_cmp_ne_u32_e32 vcc, v6, v4
	s_and_saveexec_b64 s[0:1], vcc
	s_xor_b64 s[8:9], exec, s[0:1]
	s_cbranch_execz .LBB0_844
	buffer_inv sc1
	s_waitcnt vmcnt(0)
	s_add_u32 s20, s4, 0x3500
	s_addc_u32 s21, s5, 0
	v_mov_b64_e32 v[4:5], s[20:21]
	flat_load_dword v0, v[4:5] sc1
	s_waitcnt vmcnt(0) lgkmcnt(0)
	v_cmp_eq_u32_e32 vcc, v0, v3
	s_and_saveexec_b64 s[12:13], vcc
	s_cbranch_execz .LBB0_843
	s_mov_b32 s45, 1
	s_mov_b64 s[6:7], 0
	s_branch .LBB0_835

; __device__ __forceinline__ unsigned xb_ld(unsigned* p)              { return __hip_atomic_load(p, __ATOMIC_RELAXED, __HIP_MEMORY_SCOPE_AGENT); }
; __device__ __forceinline__ unsigned xb_add(unsigned* p, unsigned v) { return __hip_atomic_fetch_add(p, v, __ATOMIC_RELAXED, __HIP_MEMORY_SCOPE_AGENT); }
; #define XB_SPIN(cond, bar) do { unsigned _sp = 0; while (cond) { __builtin_amdgcn_s_sleep(1); \
;     if ((++_sp & 255u) == 0u) { if (xb_ld(&(bar)[XB_TMO])) break; if (_sp > XB_SPIN_CAP) { atomicAdd(&(bar)[XB_TMO], 1u); break; } } } } while (0)
; __device__ __forceinline__ void xcd_barrier(const XcdBarrier& b) {
;     ...
;         if (old + 1u == (gen + 1u) * nloc) {
;             __builtin_amdgcn_fence(__ATOMIC_RELEASE, "agent");
;             asm volatile("s_waitcnt vmcnt(0)" ::: "memory");
;             const unsigned og = xb_add(&bar[XB_TOP], 1u);
;             const unsigned tg = og / nx;
;             if (og + 1u == (tg + 1u) * nx) xb_add(&bar[XB_TOPGEN], 1u);
;             else XB_SPIN(xb_ld(&bar[XB_TOPGEN]) == tg, bar);
.LBB0_844:
	s_andn2_saveexec_b64 s[0:1], s[8:9]
	s_cbranch_execz .LBB0_860
	v_mov_b32_e32 v2, s4
	v_add_co_u32_e32 v2, vcc, 0x3000, v2
	v_mov_b32_e32 v3, s5
	buffer_inv sc1
	buffer_wbl2 sc1
	s_waitcnt vmcnt(0)
	v_addc_co_u32_e32 v3, vcc, 0, v3, vcc
	flat_atomic_add v2, v[2:3], v223 offset:1024 sc0
	v_cvt_f32_u32_e32 v3, v0
	v_sub_u32_e32 v4, 0, v0
	s_add_u32 s8, s4, 0x3500
	s_addc_u32 s9, s5, 0
	v_rcp_iflag_f32_e32 v3, v3
	s_mov_b64 s[6:7], -1
	v_mul_f32_e32 v3, 0x4f7ffffe, v3
	v_cvt_u32_f32_e32 v3, v3
	v_mul_lo_u32 v4, v4, v3
	v_mul_hi_u32 v4, v3, v4
	v_add_u32_e32 v3, v3, v4
	s_waitcnt vmcnt(0) lgkmcnt(0)
	v_mul_hi_u32 v3, v2, v3
	v_mul_lo_u32 v4, v3, v0
	v_sub_u32_e32 v4, v2, v4
	v_cmp_ge_u32_e32 vcc, v4, v0
	v_add_u32_e32 v5, 1, v3
	s_nop 0
	v_cndmask_b32_e32 v3, v3, v5, vcc
	v_sub_u32_e32 v5, v4, v0
	v_cndmask_b32_e32 v4, v4, v5, vcc
	v_cmp_ge_u32_e32 vcc, v4, v0
	v_add_u32_e32 v4, 1, v3
	v_add_u32_e32 v5, 1, v2
	v_cndmask_b32_e32 v4, v3, v4, vcc
	v_mad_u64_u32 v[2:3], s[0:1], v0, v4, v[0:1]
	v_cmp_ne_u32_e32 vcc, v5, v2
	v_mov_b64_e32 v[2:3], s[8:9]
	s_and_saveexec_b64 s[12:13], vcc
	s_cbranch_execz .LBB0_857
	v_mov_b64_e32 v[2:3], s[8:9]
	flat_load_dword v0, v[2:3] sc1
	s_mov_b64 s[6:7], 0
	s_waitcnt vmcnt(0) lgkmcnt(0)
	v_cmp_eq_u32_e32 vcc, v0, v4
	s_and_saveexec_b64 s[22:23], vcc
	s_cbranch_execz .LBB0_856
	s_add_u32 s20, s4, 0x200
	s_addc_u32 s21, s5, 0
	s_mov_b32 s42, 1
	s_mov_b64 s[4:5], 0
	s_branch .LBB0_849
